# epilogue de-serialisation: diff-attention second-map epilogue issues its 16 gain loads together with a counted vmcnt instead of load+vmcnt(0) per store
# baseline (speedup 1.0000x reference)
.LBB0_1253:
	v_mov_b32_e32 v0, v129
	s_nop 1
	v_permlane32_swap_b32 v0, v129
	v_cndmask_b32_e64 v2, 0, 1, s[38:39]
	v_add_f32_e32 v0, v0, v129
	v_rcp_f32_e32 v0, v0
	v_cmp_ne_u32_e64 s[8:9], 1, v2
	s_andn2_b64 vcc, exec, s[38:39]
	s_mov_b64 s[38:39], -1
	s_cbranch_vccnz .LBB0_1255
	global_load_dwordx4 v[4:7], v[114:115], off offset:48
	global_load_dwordx4 v[8:11], v[114:115], off offset:32
	global_load_dwordx4 v[12:15], v[114:115], off offset:16
	global_load_dwordx4 v[80:83], v[114:115], off
	global_load_dwordx4 v[84:87], v[114:115], off offset:112
	global_load_dwordx4 v[88:91], v[114:115], off offset:96
	global_load_dwordx4 v[92:95], v[114:115], off offset:80
	global_load_dwordx4 v[96:99], v[114:115], off offset:64
	global_load_dwordx4 v[192:195], v[114:115], off offset:176
	global_load_dwordx4 v[196:199], v[114:115], off offset:160
	global_load_dwordx4 v[200:203], v[114:115], off offset:144
	global_load_dwordx4 v[204:207], v[114:115], off offset:128
	global_load_dwordx4 v[208:211], v[114:115], off offset:224
	global_load_dwordx4 v[212:215], v[114:115], off offset:240
	global_load_dwordx4 v[216:219], v[114:115], off offset:208
	global_load_dwordx4 v[220:223], v[114:115], off offset:192
	v_pk_mul_f32 v[2:3], v[30:31], v[0:1] op_sel_hi:[1,0]
	s_waitcnt vmcnt(2)
	v_pk_fma_f32 v[2:3], v[112:113], v[2:3], v[214:215] neg_lo:[1,0,0] neg_hi:[1,0,0]
	s_nop 0
	v_pk_mul_f32 v[214:215], v[2:3], v[2:3]
	v_pk_mul_f32 v[100:101], v[66:67], v[0:1] op_sel_hi:[1,0]
	s_nop 0
	v_pk_fma_f32 v[158:159], v[112:113], v[100:101], v[82:83] neg_lo:[1,0,0] neg_hi:[1,0,0]
	v_pk_mul_f32 v[82:83], v[64:65], v[0:1] op_sel_hi:[1,0]
	v_pk_mul_f32 v[224:225], v[158:159], v[158:159]
	v_pk_fma_f32 v[164:165], v[112:113], v[82:83], v[80:81] neg_lo:[1,0,0] neg_hi:[1,0,0]
	v_pk_mul_f32 v[80:81], v[70:71], v[0:1] op_sel_hi:[1,0]
	v_pk_mul_f32 v[226:227], v[164:165], v[164:165]
	v_pk_fma_f32 v[156:157], v[112:113], v[80:81], v[14:15] neg_lo:[1,0,0] neg_hi:[1,0,0]
	v_pk_mul_f32 v[14:15], v[68:69], v[0:1] op_sel_hi:[1,0]
	v_add_f32_e32 v129, v226, v227
	v_pk_fma_f32 v[166:167], v[112:113], v[14:15], v[12:13] neg_lo:[1,0,0] neg_hi:[1,0,0]
	v_add_f32_e32 v129, v224, v129
	v_pk_mul_f32 v[230:231], v[166:167], v[166:167]
	v_add_f32_e32 v129, v225, v129
	v_pk_mul_f32 v[12:13], v[74:75], v[0:1] op_sel_hi:[1,0]
	v_add_f32_e32 v129, v230, v129
	v_pk_mul_f32 v[228:229], v[156:157], v[156:157]
	v_pk_fma_f32 v[152:153], v[112:113], v[12:13], v[10:11] neg_lo:[1,0,0] neg_hi:[1,0,0]
	v_pk_mul_f32 v[10:11], v[72:73], v[0:1] op_sel_hi:[1,0]
	v_add_f32_e32 v129, v231, v129
	v_pk_fma_f32 v[162:163], v[112:113], v[10:11], v[8:9] neg_lo:[1,0,0] neg_hi:[1,0,0]
	v_add_f32_e32 v129, v228, v129
	v_pk_mul_f32 v[234:235], v[162:163], v[162:163]
	v_add_f32_e32 v129, v229, v129
	v_pk_mul_f32 v[8:9], v[78:79], v[0:1] op_sel_hi:[1,0]
	v_add_f32_e32 v129, v234, v129
	v_pk_mul_f32 v[232:233], v[152:153], v[152:153]
	v_pk_fma_f32 v[110:111], v[112:113], v[8:9], v[6:7] neg_lo:[1,0,0] neg_hi:[1,0,0]
	v_pk_mul_f32 v[6:7], v[76:77], v[0:1] op_sel_hi:[1,0]
	v_add_f32_e32 v129, v235, v129
	v_pk_fma_f32 v[160:161], v[112:113], v[6:7], v[4:5] neg_lo:[1,0,0] neg_hi:[1,0,0]
	v_add_f32_e32 v129, v232, v129
	v_pk_mul_f32 v[238:239], v[160:161], v[160:161]
	v_add_f32_e32 v129, v233, v129
	v_pk_mul_f32 v[4:5], v[50:51], v[0:1] op_sel_hi:[1,0]
	v_add_f32_e32 v129, v238, v129
	v_pk_mul_f32 v[236:237], v[110:111], v[110:111]
	v_pk_fma_f32 v[104:105], v[112:113], v[4:5], v[98:99] neg_lo:[1,0,0] neg_hi:[1,0,0]
	v_pk_mul_f32 v[4:5], v[48:49], v[0:1] op_sel_hi:[1,0]
	v_add_f32_e32 v129, v239, v129
	v_pk_fma_f32 v[154:155], v[112:113], v[4:5], v[96:97] neg_lo:[1,0,0] neg_hi:[1,0,0]
	v_add_f32_e32 v129, v236, v129
	v_pk_mul_f32 v[242:243], v[154:155], v[154:155]
	v_add_f32_e32 v129, v237, v129
	v_pk_mul_f32 v[4:5], v[54:55], v[0:1] op_sel_hi:[1,0]
	v_add_f32_e32 v129, v242, v129
	v_pk_mul_f32 v[240:241], v[104:105], v[104:105]
	v_pk_fma_f32 v[102:103], v[112:113], v[4:5], v[94:95] neg_lo:[1,0,0] neg_hi:[1,0,0]
	v_pk_mul_f32 v[4:5], v[52:53], v[0:1] op_sel_hi:[1,0]
	v_add_f32_e32 v129, v243, v129
	v_pk_fma_f32 v[150:151], v[112:113], v[4:5], v[92:93] neg_lo:[1,0,0] neg_hi:[1,0,0]
	v_add_f32_e32 v129, v240, v129
	v_pk_mul_f32 v[246:247], v[150:151], v[150:151]
	v_add_f32_e32 v129, v241, v129
	v_pk_mul_f32 v[4:5], v[58:59], v[0:1] op_sel_hi:[1,0]
	v_add_f32_e32 v129, v246, v129
	v_pk_mul_f32 v[244:245], v[102:103], v[102:103]
	v_pk_fma_f32 v[98:99], v[112:113], v[4:5], v[90:91] neg_lo:[1,0,0] neg_hi:[1,0,0]
	v_pk_mul_f32 v[4:5], v[56:57], v[0:1] op_sel_hi:[1,0]
	v_add_f32_e32 v129, v247, v129
	v_pk_fma_f32 v[108:109], v[112:113], v[4:5], v[88:89] neg_lo:[1,0,0] neg_hi:[1,0,0]
	v_add_f32_e32 v129, v244, v129
	v_pk_mul_f32 v[250:251], v[108:109], v[108:109]
	v_add_f32_e32 v129, v245, v129
	v_pk_mul_f32 v[4:5], v[62:63], v[0:1] op_sel_hi:[1,0]
	v_add_f32_e32 v129, v250, v129
	v_pk_mul_f32 v[248:249], v[98:99], v[98:99]
	v_pk_fma_f32 v[94:95], v[112:113], v[4:5], v[86:87] neg_lo:[1,0,0] neg_hi:[1,0,0]
	v_pk_mul_f32 v[4:5], v[60:61], v[0:1] op_sel_hi:[1,0]
	v_add_f32_e32 v129, v251, v129
	v_pk_fma_f32 v[106:107], v[112:113], v[4:5], v[84:85] neg_lo:[1,0,0] neg_hi:[1,0,0]
	v_add_f32_e32 v129, v248, v129
	v_pk_mul_f32 v[178:179], v[106:107], v[106:107]
	v_add_f32_e32 v129, v249, v129
	v_pk_mul_f32 v[4:5], v[34:35], v[0:1] op_sel_hi:[1,0]
	v_add_f32_e32 v129, v178, v129
	v_pk_mul_f32 v[252:253], v[94:95], v[94:95]
	v_pk_fma_f32 v[88:89], v[112:113], v[4:5], v[206:207] neg_lo:[1,0,0] neg_hi:[1,0,0]
	v_pk_mul_f32 v[4:5], v[32:33], v[0:1] op_sel_hi:[1,0]
	v_add_f32_e32 v129, v179, v129
	v_pk_fma_f32 v[100:101], v[112:113], v[4:5], v[204:205] neg_lo:[1,0,0] neg_hi:[1,0,0]
	v_add_f32_e32 v129, v252, v129
	v_pk_mul_f32 v[204:205], v[100:101], v[100:101]
	v_add_f32_e32 v129, v253, v129
	v_pk_mul_f32 v[4:5], v[38:39], v[0:1] op_sel_hi:[1,0]
	v_add_f32_e32 v129, v204, v129
	v_pk_mul_f32 v[206:207], v[88:89], v[88:89]
	v_pk_fma_f32 v[86:87], v[112:113], v[4:5], v[202:203] neg_lo:[1,0,0] neg_hi:[1,0,0]
	v_pk_mul_f32 v[4:5], v[36:37], v[0:1] op_sel_hi:[1,0]
	v_add_f32_e32 v129, v205, v129
	v_pk_fma_f32 v[96:97], v[112:113], v[4:5], v[200:201] neg_lo:[1,0,0] neg_hi:[1,0,0]
	v_add_f32_e32 v129, v206, v129
	v_pk_mul_f32 v[200:201], v[96:97], v[96:97]
	v_add_f32_e32 v129, v207, v129
	v_pk_mul_f32 v[4:5], v[42:43], v[0:1] op_sel_hi:[1,0]
	v_add_f32_e32 v129, v200, v129
	v_pk_mul_f32 v[202:203], v[86:87], v[86:87]
	v_pk_fma_f32 v[82:83], v[112:113], v[4:5], v[198:199] neg_lo:[1,0,0] neg_hi:[1,0,0]
	v_pk_mul_f32 v[4:5], v[40:41], v[0:1] op_sel_hi:[1,0]
	v_add_f32_e32 v129, v201, v129
	v_pk_fma_f32 v[92:93], v[112:113], v[4:5], v[196:197] neg_lo:[1,0,0] neg_hi:[1,0,0]
	v_add_f32_e32 v129, v202, v129
	v_pk_mul_f32 v[196:197], v[92:93], v[92:93]
	v_add_f32_e32 v129, v203, v129
	v_pk_mul_f32 v[4:5], v[46:47], v[0:1] op_sel_hi:[1,0]
	v_add_f32_e32 v129, v196, v129
	v_pk_mul_f32 v[198:199], v[82:83], v[82:83]
	v_pk_fma_f32 v[14:15], v[112:113], v[4:5], v[194:195] neg_lo:[1,0,0] neg_hi:[1,0,0]
	v_pk_mul_f32 v[4:5], v[44:45], v[0:1] op_sel_hi:[1,0]
	v_add_f32_e32 v129, v197, v129
	v_pk_fma_f32 v[90:91], v[112:113], v[4:5], v[192:193] neg_lo:[1,0,0] neg_hi:[1,0,0]
	v_add_f32_e32 v129, v198, v129
	v_pk_mul_f32 v[192:193], v[90:91], v[90:91]
	v_add_f32_e32 v129, v199, v129
	v_pk_mul_f32 v[4:5], v[18:19], v[0:1] op_sel_hi:[1,0]
	v_add_f32_e32 v129, v192, v129
	v_pk_mul_f32 v[194:195], v[14:15], v[14:15]
	s_waitcnt vmcnt(0)
	v_pk_fma_f32 v[10:11], v[112:113], v[4:5], v[222:223] neg_lo:[1,0,0] neg_hi:[1,0,0]
	v_pk_mul_f32 v[4:5], v[16:17], v[0:1] op_sel_hi:[1,0]
	v_add_f32_e32 v129, v193, v129
	v_pk_fma_f32 v[84:85], v[112:113], v[4:5], v[220:221] neg_lo:[1,0,0] neg_hi:[1,0,0]
	v_add_f32_e32 v129, v194, v129
	v_pk_mul_f32 v[220:221], v[84:85], v[84:85]
	v_add_f32_e32 v129, v195, v129
	v_pk_mul_f32 v[4:5], v[22:23], v[0:1] op_sel_hi:[1,0]
	v_add_f32_e32 v129, v220, v129
	v_pk_mul_f32 v[222:223], v[10:11], v[10:11]
	v_pk_fma_f32 v[8:9], v[112:113], v[4:5], v[218:219] neg_lo:[1,0,0] neg_hi:[1,0,0]
	v_pk_mul_f32 v[4:5], v[20:21], v[0:1] op_sel_hi:[1,0]
	v_add_f32_e32 v129, v221, v129
	v_pk_fma_f32 v[80:81], v[112:113], v[4:5], v[216:217] neg_lo:[1,0,0] neg_hi:[1,0,0]
	v_add_f32_e32 v129, v222, v129
	v_pk_mul_f32 v[216:217], v[80:81], v[80:81]
	v_add_f32_e32 v129, v223, v129
	v_pk_mul_f32 v[4:5], v[26:27], v[0:1] op_sel_hi:[1,0]
	v_add_f32_e32 v129, v216, v129
	v_pk_mul_f32 v[218:219], v[8:9], v[8:9]
	v_pk_fma_f32 v[6:7], v[112:113], v[4:5], v[210:211] neg_lo:[1,0,0] neg_hi:[1,0,0]
	v_pk_mul_f32 v[4:5], v[24:25], v[0:1] op_sel_hi:[1,0]
	v_add_f32_e32 v129, v217, v129
	v_pk_fma_f32 v[12:13], v[112:113], v[4:5], v[208:209] neg_lo:[1,0,0] neg_hi:[1,0,0]
	v_add_f32_e32 v129, v218, v129
	v_pk_mul_f32 v[208:209], v[12:13], v[12:13]
	v_add_f32_e32 v129, v219, v129
	v_add_f32_e32 v129, v208, v129
	v_pk_mul_f32 v[210:211], v[6:7], v[6:7]
	v_pk_mul_f32 v[4:5], v[28:29], v[0:1] op_sel_hi:[1,0]
	v_add_f32_e32 v129, v209, v129
	v_pk_fma_f32 v[4:5], v[112:113], v[4:5], v[212:213] neg_lo:[1,0,0] neg_hi:[1,0,0]
	v_add_f32_e32 v129, v210, v129
	v_pk_mul_f32 v[212:213], v[4:5], v[4:5]
	v_add_f32_e32 v129, v211, v129
	v_add_f32_e32 v129, v212, v129
	v_add_f32_e32 v129, v213, v129
	v_add_f32_e32 v129, v214, v129
	v_add_f32_e32 v129, v215, v129
	v_mov_b32_e32 v178, v129
	s_nop 1
	v_permlane32_swap_b32 v129, v178
	global_load_dwordx4 v[16:19], v[124:125], off
	global_load_dwordx4 v[20:23], v[124:125], off offset:32
	global_load_dwordx4 v[24:27], v[124:125], off offset:64
	global_load_dwordx4 v[28:31], v[124:125], off offset:96
	global_load_dwordx4 v[32:35], v[124:125], off offset:128
	global_load_dwordx4 v[36:39], v[124:125], off offset:160
	global_load_dwordx4 v[40:43], v[124:125], off offset:192
	global_load_dwordx4 v[44:47], v[124:125], off offset:224
	global_load_dwordx4 v[48:51], v[124:125], off offset:256
	global_load_dwordx4 v[52:55], v[124:125], off offset:288
	global_load_dwordx4 v[56:59], v[124:125], off offset:320
	global_load_dwordx4 v[60:63], v[124:125], off offset:352
	global_load_dwordx4 v[64:67], v[124:125], off offset:384
	global_load_dwordx4 v[68:71], v[124:125], off offset:416
	global_load_dwordx4 v[72:75], v[124:125], off offset:448
	global_load_dwordx4 v[76:79], v[124:125], off offset:480
	v_add_f32_e32 v129, v129, v178
	v_fmamk_f32 v129, v129, 0x3c000000, v177
	v_mul_f32_e32 v178, 0x4b800000, v129
	v_cmp_gt_f32_e32 vcc, s52, v129
	s_nop 1
	v_cndmask_b32_e32 v129, v129, v178, vcc
	v_rsq_f32_e32 v129, v129
	s_nop 0
	v_mul_f32_e32 v178, 0x45800000, v129
	v_cndmask_b32_e32 v129, v129, v178, vcc
	v_mul_f32_e32 v178, v189, v129
	v_pk_mul_f32 v[164:165], v[164:165], v[178:179] op_sel_hi:[1,0]
	v_pk_mul_f32 v[158:159], v[158:159], v[178:179] op_sel_hi:[1,0]
	v_pk_mul_f32 v[156:157], v[156:157], v[178:179] op_sel_hi:[1,0]
	v_pk_mul_f32 v[162:163], v[162:163], v[178:179] op_sel_hi:[1,0]
	v_pk_mul_f32 v[152:153], v[152:153], v[178:179] op_sel_hi:[1,0]
	v_pk_mul_f32 v[110:111], v[110:111], v[178:179] op_sel_hi:[1,0]
	s_waitcnt vmcnt(15)
	v_pk_mul_f32 v[164:165], v[16:17], v[164:165]
	v_pk_mul_f32 v[158:159], v[18:19], v[158:159]
	v_cvt_pk_bf16_f32 v164, v164, v165
	v_cvt_pk_bf16_f32 v165, v158, v159
	global_store_dwordx2 v[144:145], v[164:165], off
	v_pk_mul_f32 v[158:159], v[166:167], v[178:179] op_sel_hi:[1,0]
	s_waitcnt vmcnt(15)
	v_pk_mul_f32 v[156:157], v[22:23], v[156:157]
	v_pk_mul_f32 v[158:159], v[20:21], v[158:159]
	s_nop 0
	v_cvt_pk_bf16_f32 v158, v158, v159
	v_cvt_pk_bf16_f32 v159, v156, v157
	global_store_dwordx2 v[144:145], v[158:159], off offset:16
	s_waitcnt vmcnt(15)
	v_pk_mul_f32 v[156:157], v[24:25], v[162:163]
	v_pk_mul_f32 v[152:153], v[26:27], v[152:153]
	v_cvt_pk_bf16_f32 v156, v156, v157
	v_cvt_pk_bf16_f32 v157, v152, v153
	global_store_dwordx2 v[144:145], v[156:157], off offset:32
	v_pk_mul_f32 v[152:153], v[160:161], v[178:179] op_sel_hi:[1,0]
	s_waitcnt vmcnt(15)
	v_pk_mul_f32 v[110:111], v[30:31], v[110:111]
	v_pk_mul_f32 v[152:153], v[28:29], v[152:153]
	s_nop 0
	v_cvt_pk_bf16_f32 v152, v152, v153
	v_cvt_pk_bf16_f32 v153, v110, v111
	global_store_dwordx2 v[144:145], v[152:153], off offset:48
	v_pk_mul_f32 v[110:111], v[154:155], v[178:179] op_sel_hi:[1,0]
	v_pk_mul_f32 v[104:105], v[104:105], v[178:179] op_sel_hi:[1,0]
	v_pk_mul_f32 v[102:103], v[102:103], v[178:179] op_sel_hi:[1,0]
	v_pk_mul_f32 v[108:109], v[108:109], v[178:179] op_sel_hi:[1,0]
	v_pk_mul_f32 v[98:99], v[98:99], v[178:179] op_sel_hi:[1,0]
	v_pk_mul_f32 v[94:95], v[94:95], v[178:179] op_sel_hi:[1,0]
	s_waitcnt vmcnt(15)
	v_pk_mul_f32 v[110:111], v[32:33], v[110:111]
	v_pk_mul_f32 v[104:105], v[34:35], v[104:105]
	v_cvt_pk_bf16_f32 v110, v110, v111
	v_cvt_pk_bf16_f32 v111, v104, v105
	global_store_dwordx2 v[144:145], v[110:111], off offset:64
	v_pk_mul_f32 v[104:105], v[150:151], v[178:179] op_sel_hi:[1,0]
	s_waitcnt vmcnt(15)
	v_pk_mul_f32 v[102:103], v[102:103], v[38:39]
	v_pk_mul_f32 v[104:105], v[104:105], v[36:37]
	s_nop 0
	v_cvt_pk_bf16_f32 v104, v104, v105
	v_cvt_pk_bf16_f32 v105, v102, v103
	global_store_dwordx2 v[144:145], v[104:105], off offset:80
	s_waitcnt vmcnt(15)
	v_pk_mul_f32 v[102:103], v[108:109], v[40:41]
	v_pk_mul_f32 v[98:99], v[98:99], v[42:43]
	v_cvt_pk_bf16_f32 v102, v102, v103
	v_cvt_pk_bf16_f32 v103, v98, v99
	global_store_dwordx2 v[144:145], v[102:103], off offset:96
	v_pk_mul_f32 v[98:99], v[106:107], v[178:179] op_sel_hi:[1,0]
	s_waitcnt vmcnt(15)
	v_pk_mul_f32 v[94:95], v[94:95], v[46:47]
	v_pk_mul_f32 v[98:99], v[98:99], v[44:45]
	s_nop 0
	v_cvt_pk_bf16_f32 v98, v98, v99
	v_cvt_pk_bf16_f32 v99, v94, v95
	global_store_dwordx2 v[144:145], v[98:99], off offset:112
	v_pk_mul_f32 v[94:95], v[100:101], v[178:179] op_sel_hi:[1,0]
	v_pk_mul_f32 v[88:89], v[88:89], v[178:179] op_sel_hi:[1,0]
	v_pk_mul_f32 v[86:87], v[86:87], v[178:179] op_sel_hi:[1,0]
	v_pk_mul_f32 v[92:93], v[92:93], v[178:179] op_sel_hi:[1,0]
	v_pk_mul_f32 v[82:83], v[82:83], v[178:179] op_sel_hi:[1,0]
	v_pk_mul_f32 v[14:15], v[14:15], v[178:179] op_sel_hi:[1,0]
	s_waitcnt vmcnt(15)
	v_pk_mul_f32 v[94:95], v[94:95], v[48:49]
	v_pk_mul_f32 v[88:89], v[88:89], v[50:51]
	v_cvt_pk_bf16_f32 v94, v94, v95
	v_cvt_pk_bf16_f32 v95, v88, v89
	global_store_dwordx2 v[144:145], v[94:95], off offset:128
	v_pk_mul_f32 v[88:89], v[96:97], v[178:179] op_sel_hi:[1,0]
	s_waitcnt vmcnt(15)
	v_pk_mul_f32 v[86:87], v[86:87], v[54:55]
	v_pk_mul_f32 v[88:89], v[88:89], v[52:53]
	s_nop 0
	v_cvt_pk_bf16_f32 v88, v88, v89
	v_cvt_pk_bf16_f32 v89, v86, v87
	global_store_dwordx2 v[144:145], v[88:89], off offset:144
	s_waitcnt vmcnt(15)
	v_pk_mul_f32 v[86:87], v[92:93], v[56:57]
	v_pk_mul_f32 v[82:83], v[82:83], v[58:59]
	v_cvt_pk_bf16_f32 v86, v86, v87
	v_cvt_pk_bf16_f32 v87, v82, v83
	global_store_dwordx2 v[144:145], v[86:87], off offset:160
	v_pk_mul_f32 v[82:83], v[90:91], v[178:179] op_sel_hi:[1,0]
	s_waitcnt vmcnt(15)
	v_pk_mul_f32 v[14:15], v[14:15], v[62:63]
	v_pk_mul_f32 v[82:83], v[82:83], v[60:61]
	s_nop 0
	v_cvt_pk_bf16_f32 v82, v82, v83
	v_cvt_pk_bf16_f32 v83, v14, v15
	global_store_dwordx2 v[144:145], v[82:83], off offset:176
	v_pk_mul_f32 v[14:15], v[84:85], v[178:179] op_sel_hi:[1,0]
	v_pk_mul_f32 v[10:11], v[10:11], v[178:179] op_sel_hi:[1,0]
	v_pk_mul_f32 v[8:9], v[8:9], v[178:179] op_sel_hi:[1,0]
	v_pk_mul_f32 v[12:13], v[12:13], v[178:179] op_sel_hi:[1,0]
	v_pk_mul_f32 v[6:7], v[6:7], v[178:179] op_sel_hi:[1,0]
	v_pk_mul_f32 v[4:5], v[4:5], v[178:179] op_sel_hi:[1,0]
	v_pk_mul_f32 v[2:3], v[2:3], v[178:179] op_sel_hi:[1,0]
	s_waitcnt vmcnt(15)
	v_pk_mul_f32 v[14:15], v[14:15], v[64:65]
	v_pk_mul_f32 v[10:11], v[10:11], v[66:67]
	v_cvt_pk_bf16_f32 v14, v14, v15
	v_cvt_pk_bf16_f32 v15, v10, v11
	global_store_dwordx2 v[144:145], v[14:15], off offset:192
	v_pk_mul_f32 v[10:11], v[80:81], v[178:179] op_sel_hi:[1,0]
	s_waitcnt vmcnt(15)
	v_pk_mul_f32 v[8:9], v[8:9], v[70:71]
	v_pk_mul_f32 v[10:11], v[10:11], v[68:69]
	s_nop 0
	v_cvt_pk_bf16_f32 v10, v10, v11
	v_cvt_pk_bf16_f32 v11, v8, v9
	global_store_dwordx2 v[144:145], v[10:11], off offset:208
	s_waitcnt vmcnt(15)
	v_pk_mul_f32 v[8:9], v[12:13], v[72:73]
	v_pk_mul_f32 v[6:7], v[6:7], v[74:75]
	v_cvt_pk_bf16_f32 v8, v8, v9
	v_cvt_pk_bf16_f32 v9, v6, v7
	global_store_dwordx2 v[144:145], v[8:9], off offset:224
	s_waitcnt vmcnt(15)
	v_pk_mul_f32 v[4:5], v[4:5], v[76:77]
	v_pk_mul_f32 v[2:3], v[2:3], v[78:79]
	v_cvt_pk_bf16_f32 v4, v4, v5
	v_cvt_pk_bf16_f32 v5, v2, v3
	global_store_dwordx2 v[144:145], v[4:5], off offset:240
	s_cbranch_execnz .LBB0_1219
	s_branch .LBB0_1256
